# P0 a_w_in bf16 conversion loop hand-written: 16B loads, two items per trip
# speedup vs baseline: 1.0052x; 1.0033x over previous
.Lcv0_entry:
	s_waitcnt lgkmcnt(0)
	s_mul_i32 s12, s54, 0x2100
	s_add_i32 s12, s12, 0x8200
	v_mbcnt_lo_u32_b32 v113, -1, 0
	v_mbcnt_hi_u32_b32 v113, -1, v113
	v_lshrrev_b32_e32 v114, 3, v113
	v_and_b32_e32 v115, 7, v113
	v_mul_u32_u24_e32 v22, 0x84, v114
	v_lshl_add_u32 v22, v115, 4, v22
	v_add_u32_e32 v22, s12, v22
	v_mul_u32_u24_e32 v23, 0x420, v115
	v_lshl_add_u32 v23, v114, 2, v23
	v_add_u32_e32 v23, s12, v23
	v_lshlrev_b32_e32 v24, 11, v114
	v_lshl_add_u32 v24, v115, 4, v24
	v_mov_b32_e32 v25, 0
	v_mov_b32_e32 v27, 0
	v_mul_u32_u24_e32 v116, 0x5040, v114
	v_lshl_add_u32 v116, v115, 4, v116
	s_mov_b32 s100, 0x28200
	s_mov_b32 s101, 0
	s_mov_b32 s17, s22
.Lcv0_loop:
	s_lshr_b32 s12, s17, 5
	s_mul_i32 s12, s12, 0xcccd
	s_lshr_b32 s13, s12, 18
	s_mul_i32 s12, s13, 0xa0
	s_sub_i32 s20, s17, s12
	s_mov_b32 s21, 0
	s_mov_b32 s16, 0
	s_mov_b32 s18, s20
	s_cmp_lt_u32 s20, 16
	s_cbranch_scc1 .Lcv0A_sel
	s_movk_i32 s21, 0x200
	s_movk_i32 s16, 0x200
	s_add_i32 s18, s20, -16
	s_cmp_lt_u32 s20, 32
	s_cbranch_scc1 .Lcv0A_sel
	s_movk_i32 s21, 0xc00
	s_movk_i32 s16, 0x400
	s_add_i32 s18, s20, -32
	s_cmpk_lt_u32 s20, 0x60
	s_cbranch_scc1 .Lcv0A_sel
	s_movk_i32 s21, 0x400
	s_movk_i32 s16, 0xc00
	s_add_i32 s18, s20, 0xffffffa0
.Lcv0A_sel:
	s_lshl_b32 s12, s13, 6
	s_mul_i32 s12, s12, 0x5040
	s_lshl_b32 s20, s18, 5
	s_add_i32 s20, s20, s21
	s_lshl_b32 s20, s20, 2
	s_add_u32 s12, s12, s20
	s_add_u32 s98, s4, s12
	s_addc_u32 s99, s5, 0
	v_mov_b32_e32 v26, v116
	v_lshl_add_u64 v[20:21], s[98:99], 0, v[26:27]
	global_load_dwordx4 v[32:35], v[20:21], off
	v_lshl_add_u64 v[20:21], s[100:101], 0, v[20:21]
	global_load_dwordx4 v[36:39], v[20:21], off
	v_lshl_add_u64 v[20:21], s[100:101], 0, v[20:21]
	global_load_dwordx4 v[40:43], v[20:21], off
	v_lshl_add_u64 v[20:21], s[100:101], 0, v[20:21]
	global_load_dwordx4 v[44:47], v[20:21], off
	v_lshl_add_u64 v[20:21], s[100:101], 0, v[20:21]
	global_load_dwordx4 v[48:51], v[20:21], off
	v_lshl_add_u64 v[20:21], s[100:101], 0, v[20:21]
	global_load_dwordx4 v[52:55], v[20:21], off
	v_lshl_add_u64 v[20:21], s[100:101], 0, v[20:21]
	global_load_dwordx4 v[56:59], v[20:21], off
	v_lshl_add_u64 v[20:21], s[100:101], 0, v[20:21]
	global_load_dwordx4 v[60:63], v[20:21], off
	s_lshl_b32 s12, s18, 5
	s_add_i32 s12, s12, s16
	s_lshl_b32 s12, s12, 11
	s_lshl_b32 s20, s13, 7
	s_add_u32 s12, s12, s20
	s_add_u32 s98, s8, s12
	s_addc_u32 s99, s9, 0
	v_lshl_add_u64 v[28:29], s[98:99], 0, v[24:25]
	s_add_i32 s19, s17, s80
	s_cmpk_lt_i32 s19, 0xa00
	s_cbranch_scc0 .Lcv0_single
	s_lshr_b32 s12, s19, 5
	s_mul_i32 s12, s12, 0xcccd
	s_lshr_b32 s13, s12, 18
	s_mul_i32 s12, s13, 0xa0
	s_sub_i32 s20, s19, s12
	s_mov_b32 s21, 0
	s_mov_b32 s16, 0
	s_mov_b32 s18, s20
	s_cmp_lt_u32 s20, 16
	s_cbranch_scc1 .Lcv0B_sel
	s_movk_i32 s21, 0x200
	s_movk_i32 s16, 0x200
	s_add_i32 s18, s20, -16
	s_cmp_lt_u32 s20, 32
	s_cbranch_scc1 .Lcv0B_sel
	s_movk_i32 s21, 0xc00
	s_movk_i32 s16, 0x400
	s_add_i32 s18, s20, -32
	s_cmpk_lt_u32 s20, 0x60
	s_cbranch_scc1 .Lcv0B_sel
	s_movk_i32 s21, 0x400
	s_movk_i32 s16, 0xc00
	s_add_i32 s18, s20, 0xffffffa0
.Lcv0B_sel:
	s_lshl_b32 s12, s13, 6
	s_mul_i32 s12, s12, 0x5040
	s_lshl_b32 s20, s18, 5
	s_add_i32 s20, s20, s21
	s_lshl_b32 s20, s20, 2
	s_add_u32 s12, s12, s20
	s_add_u32 s98, s4, s12
	s_addc_u32 s99, s5, 0
	v_mov_b32_e32 v26, v116
	v_lshl_add_u64 v[20:21], s[98:99], 0, v[26:27]
	global_load_dwordx4 v[64:67], v[20:21], off
	v_lshl_add_u64 v[20:21], s[100:101], 0, v[20:21]
	global_load_dwordx4 v[68:71], v[20:21], off
	v_lshl_add_u64 v[20:21], s[100:101], 0, v[20:21]
	global_load_dwordx4 v[72:75], v[20:21], off
	v_lshl_add_u64 v[20:21], s[100:101], 0, v[20:21]
	global_load_dwordx4 v[76:79], v[20:21], off
	v_lshl_add_u64 v[20:21], s[100:101], 0, v[20:21]
	global_load_dwordx4 v[80:83], v[20:21], off
	v_lshl_add_u64 v[20:21], s[100:101], 0, v[20:21]
	global_load_dwordx4 v[84:87], v[20:21], off
	v_lshl_add_u64 v[20:21], s[100:101], 0, v[20:21]
	global_load_dwordx4 v[88:91], v[20:21], off
	v_lshl_add_u64 v[20:21], s[100:101], 0, v[20:21]
	global_load_dwordx4 v[92:95], v[20:21], off
	s_lshl_b32 s12, s18, 5
	s_add_i32 s12, s12, s16
	s_lshl_b32 s12, s12, 11
	s_lshl_b32 s20, s13, 7
	s_add_u32 s12, s12, s20
	s_add_u32 s98, s8, s12
	s_addc_u32 s99, s9, 0
	v_lshl_add_u64 v[30:31], s[98:99], 0, v[24:25]
	s_waitcnt vmcnt(8)
	ds_write_b32 v22, v32 offset:0
	ds_write_b32 v22, v33 offset:4
	ds_write_b32 v22, v34 offset:8
	ds_write_b32 v22, v35 offset:12
	ds_write_b32 v22, v36 offset:1056
	ds_write_b32 v22, v37 offset:1060
	ds_write_b32 v22, v38 offset:1064
	ds_write_b32 v22, v39 offset:1068
	ds_write_b32 v22, v40 offset:2112
	ds_write_b32 v22, v41 offset:2116
	ds_write_b32 v22, v42 offset:2120
	ds_write_b32 v22, v43 offset:2124
	ds_write_b32 v22, v44 offset:3168
	ds_write_b32 v22, v45 offset:3172
	ds_write_b32 v22, v46 offset:3176
	ds_write_b32 v22, v47 offset:3180
	ds_write_b32 v22, v48 offset:4224
	ds_write_b32 v22, v49 offset:4228
	ds_write_b32 v22, v50 offset:4232
	ds_write_b32 v22, v51 offset:4236
	ds_write_b32 v22, v52 offset:5280
	ds_write_b32 v22, v53 offset:5284
	ds_write_b32 v22, v54 offset:5288
	ds_write_b32 v22, v55 offset:5292
	ds_write_b32 v22, v56 offset:6336
	ds_write_b32 v22, v57 offset:6340
	ds_write_b32 v22, v58 offset:6344
	ds_write_b32 v22, v59 offset:6348
	ds_write_b32 v22, v60 offset:7392
	ds_write_b32 v22, v61 offset:7396
	ds_write_b32 v22, v62 offset:7400
	ds_write_b32 v22, v63 offset:7404
	s_waitcnt lgkmcnt(0)
	ds_read_b32 v32, v23 offset:0
	ds_read_b32 v33, v23 offset:132
	ds_read_b32 v34, v23 offset:264
	ds_read_b32 v35, v23 offset:396
	ds_read_b32 v36, v23 offset:528
	ds_read_b32 v37, v23 offset:660
	ds_read_b32 v38, v23 offset:792
	ds_read_b32 v39, v23 offset:924
	s_waitcnt lgkmcnt(0)
	v_cvt_pk_bf16_f32 v96, v32, v33
	v_cvt_pk_bf16_f32 v97, v34, v35
	v_cvt_pk_bf16_f32 v98, v36, v37
	v_cvt_pk_bf16_f32 v99, v38, v39
	global_store_dwordx4 v[28:29], v[96:99], off
	v_add_co_u32_e32 v28, vcc, 0x4000, v28
	s_nop 1
	v_addc_co_u32_e32 v29, vcc, 0, v29, vcc
	ds_read_b32 v32, v23 offset:32
	ds_read_b32 v33, v23 offset:164
	ds_read_b32 v34, v23 offset:296
	ds_read_b32 v35, v23 offset:428
	ds_read_b32 v36, v23 offset:560
	ds_read_b32 v37, v23 offset:692
	ds_read_b32 v38, v23 offset:824
	ds_read_b32 v39, v23 offset:956
	s_waitcnt lgkmcnt(0)
	v_cvt_pk_bf16_f32 v100, v32, v33
	v_cvt_pk_bf16_f32 v101, v34, v35
	v_cvt_pk_bf16_f32 v102, v36, v37
	v_cvt_pk_bf16_f32 v103, v38, v39
	global_store_dwordx4 v[28:29], v[100:103], off
	v_add_co_u32_e32 v28, vcc, 0x4000, v28
	s_nop 1
	v_addc_co_u32_e32 v29, vcc, 0, v29, vcc
	ds_read_b32 v32, v23 offset:64
	ds_read_b32 v33, v23 offset:196
	ds_read_b32 v34, v23 offset:328
	ds_read_b32 v35, v23 offset:460
	ds_read_b32 v36, v23 offset:592
	ds_read_b32 v37, v23 offset:724
	ds_read_b32 v38, v23 offset:856
	ds_read_b32 v39, v23 offset:988
	s_waitcnt lgkmcnt(0)
	v_cvt_pk_bf16_f32 v104, v32, v33
	v_cvt_pk_bf16_f32 v105, v34, v35
	v_cvt_pk_bf16_f32 v106, v36, v37
	v_cvt_pk_bf16_f32 v107, v38, v39
	global_store_dwordx4 v[28:29], v[104:107], off
	v_add_co_u32_e32 v28, vcc, 0x4000, v28
	s_nop 1
	v_addc_co_u32_e32 v29, vcc, 0, v29, vcc
	ds_read_b32 v32, v23 offset:96
	ds_read_b32 v33, v23 offset:228
	ds_read_b32 v34, v23 offset:360
	ds_read_b32 v35, v23 offset:492
	ds_read_b32 v36, v23 offset:624
	ds_read_b32 v37, v23 offset:756
	ds_read_b32 v38, v23 offset:888
	ds_read_b32 v39, v23 offset:1020
	s_waitcnt lgkmcnt(0)
	v_cvt_pk_bf16_f32 v108, v32, v33
	v_cvt_pk_bf16_f32 v109, v34, v35
	v_cvt_pk_bf16_f32 v110, v36, v37
	v_cvt_pk_bf16_f32 v111, v38, v39
	global_store_dwordx4 v[28:29], v[108:111], off
	s_waitcnt vmcnt(4)
	ds_write_b32 v22, v64 offset:0
	ds_write_b32 v22, v65 offset:4
	ds_write_b32 v22, v66 offset:8
	ds_write_b32 v22, v67 offset:12
	ds_write_b32 v22, v68 offset:1056
	ds_write_b32 v22, v69 offset:1060
	ds_write_b32 v22, v70 offset:1064
	ds_write_b32 v22, v71 offset:1068
	ds_write_b32 v22, v72 offset:2112
	ds_write_b32 v22, v73 offset:2116
	ds_write_b32 v22, v74 offset:2120
	ds_write_b32 v22, v75 offset:2124
	ds_write_b32 v22, v76 offset:3168
	ds_write_b32 v22, v77 offset:3172
	ds_write_b32 v22, v78 offset:3176
	ds_write_b32 v22, v79 offset:3180
	ds_write_b32 v22, v80 offset:4224
	ds_write_b32 v22, v81 offset:4228
	ds_write_b32 v22, v82 offset:4232
	ds_write_b32 v22, v83 offset:4236
	ds_write_b32 v22, v84 offset:5280
	ds_write_b32 v22, v85 offset:5284
	ds_write_b32 v22, v86 offset:5288
	ds_write_b32 v22, v87 offset:5292
	ds_write_b32 v22, v88 offset:6336
	ds_write_b32 v22, v89 offset:6340
	ds_write_b32 v22, v90 offset:6344
	ds_write_b32 v22, v91 offset:6348
	ds_write_b32 v22, v92 offset:7392
	ds_write_b32 v22, v93 offset:7396
	ds_write_b32 v22, v94 offset:7400
	ds_write_b32 v22, v95 offset:7404
	s_waitcnt lgkmcnt(0)
	ds_read_b32 v64, v23 offset:0
	ds_read_b32 v65, v23 offset:132
	ds_read_b32 v66, v23 offset:264
	ds_read_b32 v67, v23 offset:396
	ds_read_b32 v68, v23 offset:528
	ds_read_b32 v69, v23 offset:660
	ds_read_b32 v70, v23 offset:792
	ds_read_b32 v71, v23 offset:924
	s_waitcnt lgkmcnt(0)
	v_cvt_pk_bf16_f32 v96, v64, v65
	v_cvt_pk_bf16_f32 v97, v66, v67
	v_cvt_pk_bf16_f32 v98, v68, v69
	v_cvt_pk_bf16_f32 v99, v70, v71
	global_store_dwordx4 v[30:31], v[96:99], off
	v_add_co_u32_e32 v30, vcc, 0x4000, v30
	s_nop 1
	v_addc_co_u32_e32 v31, vcc, 0, v31, vcc
	ds_read_b32 v64, v23 offset:32
	ds_read_b32 v65, v23 offset:164
	ds_read_b32 v66, v23 offset:296
	ds_read_b32 v67, v23 offset:428
	ds_read_b32 v68, v23 offset:560
	ds_read_b32 v69, v23 offset:692
	ds_read_b32 v70, v23 offset:824
	ds_read_b32 v71, v23 offset:956
	s_waitcnt lgkmcnt(0)
	v_cvt_pk_bf16_f32 v100, v64, v65
	v_cvt_pk_bf16_f32 v101, v66, v67
	v_cvt_pk_bf16_f32 v102, v68, v69
	v_cvt_pk_bf16_f32 v103, v70, v71
	global_store_dwordx4 v[30:31], v[100:103], off
	v_add_co_u32_e32 v30, vcc, 0x4000, v30
	s_nop 1
	v_addc_co_u32_e32 v31, vcc, 0, v31, vcc
	ds_read_b32 v64, v23 offset:64
	ds_read_b32 v65, v23 offset:196
	ds_read_b32 v66, v23 offset:328
	ds_read_b32 v67, v23 offset:460
	ds_read_b32 v68, v23 offset:592
	ds_read_b32 v69, v23 offset:724
	ds_read_b32 v70, v23 offset:856
	ds_read_b32 v71, v23 offset:988
	s_waitcnt lgkmcnt(0)
	v_cvt_pk_bf16_f32 v104, v64, v65
	v_cvt_pk_bf16_f32 v105, v66, v67
	v_cvt_pk_bf16_f32 v106, v68, v69
	v_cvt_pk_bf16_f32 v107, v70, v71
	global_store_dwordx4 v[30:31], v[104:107], off
	v_add_co_u32_e32 v30, vcc, 0x4000, v30
	s_nop 1
	v_addc_co_u32_e32 v31, vcc, 0, v31, vcc
	ds_read_b32 v64, v23 offset:96
	ds_read_b32 v65, v23 offset:228
	ds_read_b32 v66, v23 offset:360
	ds_read_b32 v67, v23 offset:492
	ds_read_b32 v68, v23 offset:624
	ds_read_b32 v69, v23 offset:756
	ds_read_b32 v70, v23 offset:888
	ds_read_b32 v71, v23 offset:1020
	s_waitcnt lgkmcnt(0)
	v_cvt_pk_bf16_f32 v108, v64, v65
	v_cvt_pk_bf16_f32 v109, v66, v67
	v_cvt_pk_bf16_f32 v110, v68, v69
	v_cvt_pk_bf16_f32 v111, v70, v71
	global_store_dwordx4 v[30:31], v[108:111], off
	s_add_i32 s17, s19, s80
	s_cmpk_lt_i32 s17, 0xa00
	s_cbranch_scc1 .Lcv0_loop
	s_branch .LBB0_22
.Lcv0_single:
	s_waitcnt vmcnt(0)
	ds_write_b32 v22, v32 offset:0
	ds_write_b32 v22, v33 offset:4
	ds_write_b32 v22, v34 offset:8
	ds_write_b32 v22, v35 offset:12
	ds_write_b32 v22, v36 offset:1056
	ds_write_b32 v22, v37 offset:1060
	ds_write_b32 v22, v38 offset:1064
	ds_write_b32 v22, v39 offset:1068
	ds_write_b32 v22, v40 offset:2112
	ds_write_b32 v22, v41 offset:2116
	ds_write_b32 v22, v42 offset:2120
	ds_write_b32 v22, v43 offset:2124
	ds_write_b32 v22, v44 offset:3168
	ds_write_b32 v22, v45 offset:3172
	ds_write_b32 v22, v46 offset:3176
	ds_write_b32 v22, v47 offset:3180
	ds_write_b32 v22, v48 offset:4224
	ds_write_b32 v22, v49 offset:4228
	ds_write_b32 v22, v50 offset:4232
	ds_write_b32 v22, v51 offset:4236
	ds_write_b32 v22, v52 offset:5280
	ds_write_b32 v22, v53 offset:5284
	ds_write_b32 v22, v54 offset:5288
	ds_write_b32 v22, v55 offset:5292
	ds_write_b32 v22, v56 offset:6336
	ds_write_b32 v22, v57 offset:6340
	ds_write_b32 v22, v58 offset:6344
	ds_write_b32 v22, v59 offset:6348
	ds_write_b32 v22, v60 offset:7392
	ds_write_b32 v22, v61 offset:7396
	ds_write_b32 v22, v62 offset:7400
	ds_write_b32 v22, v63 offset:7404
	s_waitcnt lgkmcnt(0)
	ds_read_b32 v32, v23 offset:0
	ds_read_b32 v33, v23 offset:132
	ds_read_b32 v34, v23 offset:264
	ds_read_b32 v35, v23 offset:396
	ds_read_b32 v36, v23 offset:528
	ds_read_b32 v37, v23 offset:660
	ds_read_b32 v38, v23 offset:792
	ds_read_b32 v39, v23 offset:924
	s_waitcnt lgkmcnt(0)
	v_cvt_pk_bf16_f32 v96, v32, v33
	v_cvt_pk_bf16_f32 v97, v34, v35
	v_cvt_pk_bf16_f32 v98, v36, v37
	v_cvt_pk_bf16_f32 v99, v38, v39
	global_store_dwordx4 v[28:29], v[96:99], off
	v_add_co_u32_e32 v28, vcc, 0x4000, v28
	s_nop 1
	v_addc_co_u32_e32 v29, vcc, 0, v29, vcc
	ds_read_b32 v32, v23 offset:32
	ds_read_b32 v33, v23 offset:164
	ds_read_b32 v34, v23 offset:296
	ds_read_b32 v35, v23 offset:428
	ds_read_b32 v36, v23 offset:560
	ds_read_b32 v37, v23 offset:692
	ds_read_b32 v38, v23 offset:824
	ds_read_b32 v39, v23 offset:956
	s_waitcnt lgkmcnt(0)
	v_cvt_pk_bf16_f32 v100, v32, v33
	v_cvt_pk_bf16_f32 v101, v34, v35
	v_cvt_pk_bf16_f32 v102, v36, v37
	v_cvt_pk_bf16_f32 v103, v38, v39
	global_store_dwordx4 v[28:29], v[100:103], off
	v_add_co_u32_e32 v28, vcc, 0x4000, v28
	s_nop 1
	v_addc_co_u32_e32 v29, vcc, 0, v29, vcc
	ds_read_b32 v32, v23 offset:64
	ds_read_b32 v33, v23 offset:196
	ds_read_b32 v34, v23 offset:328
	ds_read_b32 v35, v23 offset:460
	ds_read_b32 v36, v23 offset:592
	ds_read_b32 v37, v23 offset:724
	ds_read_b32 v38, v23 offset:856
	ds_read_b32 v39, v23 offset:988
	s_waitcnt lgkmcnt(0)
	v_cvt_pk_bf16_f32 v104, v32, v33
	v_cvt_pk_bf16_f32 v105, v34, v35
	v_cvt_pk_bf16_f32 v106, v36, v37
	v_cvt_pk_bf16_f32 v107, v38, v39
	global_store_dwordx4 v[28:29], v[104:107], off
	v_add_co_u32_e32 v28, vcc, 0x4000, v28
	s_nop 1
	v_addc_co_u32_e32 v29, vcc, 0, v29, vcc
	ds_read_b32 v32, v23 offset:96
	ds_read_b32 v33, v23 offset:228
	ds_read_b32 v34, v23 offset:360
	ds_read_b32 v35, v23 offset:492
	ds_read_b32 v36, v23 offset:624
	ds_read_b32 v37, v23 offset:756
	ds_read_b32 v38, v23 offset:888
	ds_read_b32 v39, v23 offset:1020
	s_waitcnt lgkmcnt(0)
	v_cvt_pk_bf16_f32 v108, v32, v33
	v_cvt_pk_bf16_f32 v109, v34, v35
	v_cvt_pk_bf16_f32 v110, v36, v37
	v_cvt_pk_bf16_f32 v111, v38, v39
	global_store_dwordx4 v[28:29], v[108:111], off
	s_branch .LBB0_22
